# hy_transpose software-pipelined by hand: next tile's global loads in flight during this tile's compute; conv weights loaded at the tile top
# speedup vs baseline: 1.0496x; 1.0046x over previous
; #define TIDX tid_opaque()
; __device__ __forceinline__ u32x4 zero4() { unsigned z = 0; asm volatile("" : "+v"(z)); return (u32x4){z, z, z, z}; }
; __device__ __forceinline__ unsigned cvt_pk_bf16(float lo, float hi) { const f32x2_t v = {lo, hi}; const bf16x2_t b = __builtin_convertvector(v, bf16x2_t); return __builtin_bit_cast(unsigned, b); }
; __device__ void hy_transpose_phase(unsigned char* smem, const Params& p, int l) {
;     ...
;     const bf16_t* uhy = (const bf16_t*)(((unsigned char*)ldp(38)) + OFF_A); bf16_t* hyT = (bf16_t*)(((unsigned char*)ldp(38)) + OFF_B);
;     const float* cw = ((const float*)ldp(7)) + (size_t)l * 3 * HYC; const float* cb = ((const float*)ldp(8)) + (size_t)l * HYC;
;     const int tid = TIDX;
;     const int ntile = (MT / 64) * (HYC / 64);
;     for (int t = blockIdx.x; t < ntile; t += gridDim.x) {
;         const int cblk = t % (HYC / 64), rblk = t / (HYC / 64); const int b = rblk >> 5, t0 = (rblk & 31) * 64, c0 = cblk * 64;
;         __syncthreads();
;         for (int e = tid; e < 66 * 8; e += 512) { const int rr = e >> 3, c8 = e & 7; const int tt = t0 - 1 + rr;
;             u32x4 v = zero4();
;             if (tt >= 0 && tt < SEQ) v = *(const u32x4*)(uhy + ((size_t)b * SEQ + tt) * HYC + c0 + c8 * 8);
;     ...
;         { const int cc = tid >> 3, t8 = tid & 7, c = c0 + cc; const float w0 = cw[c], w1 = cw[HYC + c], w2 = cw[2 * HYC + c], bb = cb[c];
;           float x[10];
; #pragma unroll
;           for (int i = 0; i < 10; ++i) x[i] = tile[(t8 * 8 + i) * 65 + cc];
;           float o[8];
; #pragma unroll
;           for (int i = 0; i < 8; ++i) o[i] = w0 * x[i] + w1 * x[i + 1] + w2 * x[i + 2] + bb;
;           u32x4 w; w.x = cvt_pk_bf16(o[0], o[1]); w.y = cvt_pk_bf16(o[2], o[3]); w.z = cvt_pk_bf16(o[4], o[5]); w.w = cvt_pk_bf16(o[6], o[7]);
;           *(u32x4*)(hyT + ((size_t)c * NB + b) * SEQ + t0 + t8 * 8) = w; }
.LBB0_248:
	s_or_b64 exec, exec, s[6:7]
	s_and_b32 s5, s30, 0xffff
	s_cmp_lg_u32 s40, -1
	s_cselect_b32 s0, s40, 0
	s_cselect_b32 s1, s41, 0
	v_mov_b64_e32 v[0:1], s[0:1]
	s_add_i32 s0, 0, 0x23e38
	s_cmp_lg_u32 s0, -1
	s_cselect_b32 s0, s0, 0
	s_cselect_b32 s1, s41, 0
	v_mov_b32_e32 v4, s0
	s_add_i32 s0, 0, 0x23e40
	s_cmp_lg_u32 s0, -1
	v_mov_b32_e32 v5, s1
	s_cselect_b32 s0, s0, 0
	s_cselect_b32 s1, s41, 0
	v_mov_b32_e32 v6, s0
	v_mov_b32_e32 v7, s1
	flat_load_dwordx2 v[2:3], v[0:1] sc0 sc1
	s_waitcnt vmcnt(0)
	flat_load_dwordx2 v[0:1], v[0:1] sc0 sc1
	s_waitcnt vmcnt(0)
	v_readlane_b32 s0, v254, 46
	flat_load_dwordx2 v[4:5], v[4:5] sc0 sc1
	s_waitcnt vmcnt(0)
	v_readlane_b32 s1, v254, 47
	flat_load_dwordx2 v[8:9], v[6:7] sc0 sc1
	s_waitcnt vmcnt(0)
	v_mov_b32_e32 v7, v234
	s_andn2_b64 vcc, exec, s[0:1]
	s_waitcnt lgkmcnt(0)
	v_readfirstlane_b32 s13, v3
	v_readfirstlane_b32 s12, v2
	v_readfirstlane_b32 s7, v1
	v_readfirstlane_b32 s6, v0
	v_readfirstlane_b32 s1, v5
	v_readfirstlane_b32 s8, v4
	v_readfirstlane_b32 s0, v9
	v_readfirstlane_b32 s10, v8
	s_cbranch_vccnz .LBB0_259
	s_add_u32 s6, s6, 0x12c00000
	s_mul_i32 s9, s5, 0x4800
	s_addc_u32 s7, s7, 0
	s_add_u32 s8, s8, s9
	v_and_b32_e32 v6, 7, v7
	s_mul_i32 s11, s5, 0x1800
	s_addc_u32 s9, s1, 0
	v_lshlrev_b32_e32 v0, 3, v7
	v_lshlrev_b32_e32 v184, 4, v6
	s_add_u32 s10, s10, s11
	v_ashrrev_i32_e32 v10, 3, v7
	v_and_b32_e32 v0, 56, v0
	v_lshl_add_u64 v[2:3], s[12:13], 0, v[184:185]
	s_mov_b64 s[12:13], 0x7c00000
	s_addc_u32 s11, s0, 0
	s_movk_i32 s0, 0x20f
	v_lshl_add_u32 v1, v10, 2, 0
	v_lshl_add_u64 v[4:5], v[2:3], 0, s[12:13]
	v_mul_u32_u24_e32 v2, 0x104, v0
	v_cmp_lt_i32_e64 s[0:1], s0, v7
	v_lshl_add_u32 v6, v6, 5, 0
	v_add_u32_e32 v11, v1, v2
	v_lshlrev_b32_e32 v184, 1, v0
	s_mov_b32 s15, s2
	s_mov_b32 s98, s2
	v_readfirstlane_b32 s31, v7
	s_mul_hi_i32 s99, s98, 0x2aaaaaab
	s_lshr_b32 s100, s99, 31
	s_ashr_i32 s99, s99, 2
	s_add_i32 s99, s99, s100
	s_mul_i32 s100, s99, 24
	s_sub_i32 s100, s98, s100
	s_lshl_b32 s100, s100, 7
	s_lshl_b32 s101, s99, 6
	s_and_b32 s101, s101, 0x7c0
	s_add_i32 s101, s101, -1
	s_ashr_i32 s99, s99, 5
	s_lshl_b32 s99, s99, 11
	v_add_u32_e32 v44, s101, v10
	v_add_u32_e32 v45, s99, v44
	v_mul_u32_u24_e32 v45, 0xc00, v45
	v_add_u32_e32 v46, s100, v45
	v_mov_b32_e32 v47, 0
	v_mov_b32_e32 v36, 0
	v_mov_b32_e32 v37, 0
	v_mov_b32_e32 v38, 0
	v_mov_b32_e32 v39, 0
	v_lshl_add_u64 v[46:47], v[4:5], 0, v[46:47]
	v_cmp_gt_u32_e32 vcc, 0x800, v44
	s_and_saveexec_b64 s[28:29], vcc
	global_load_dwordx4 v[36:39], v[46:47], off
	s_mov_b64 exec, s[28:29]
	s_cmp_lt_u32 s31, 64
	s_cbranch_scc0 .Lhyt_pf2_a
	v_add_u32_e32 v44, 64, v44
	v_add_u32_e32 v45, s99, v44
	v_mul_u32_u24_e32 v45, 0xc00, v45
	v_add_u32_e32 v46, s100, v45
	v_mov_b32_e32 v47, 0
	v_mov_b32_e32 v40, 0
	v_mov_b32_e32 v41, 0
	v_mov_b32_e32 v42, 0
	v_mov_b32_e32 v43, 0
	v_lshl_add_u64 v[46:47], v[4:5], 0, v[46:47]
	v_cmp_gt_u32_e32 vcc, 0x800, v44
	v_cmp_gt_u32_e64 s[34:35], 16, v7
	s_and_b64 vcc, vcc, s[34:35]
	s_and_saveexec_b64 s[28:29], vcc
	global_load_dwordx4 v[40:43], v[46:47], off
	s_mov_b64 exec, s[28:29]
.Lhyt_pf2_a:
	s_branch .LBB0_252
.LBB0_251:
	s_or_b64 exec, exec, s[18:19]
	v_add_u32_e32 v2, s16, v10
	v_ashrrev_i32_e32 v3, 31, v2
	s_waitcnt lgkmcnt(0)
	s_barrier
	v_add_u32_e32 v9, 0x400, v11
	ds_read2_b32 v[18:19], v11 offset1:65
	ds_read2_b32 v[20:21], v11 offset0:130 offset1:195
	v_add_u32_e32 v13, 0x800, v11
	ds_read2_b32 v[22:23], v9 offset0:4 offset1:69
	ds_read2_b32 v[24:25], v9 offset0:134 offset1:199
	ds_read2_b32 v[26:27], v13 offset0:8 offset1:73
	v_lshlrev_b64 v[2:3], 16, v[2:3]
	v_lshlrev_b64 v[0:1], 12, v[0:1]
	v_lshl_add_u64 v[2:3], s[6:7], 0, v[2:3]
	s_lshl_b32 s24, s24, 1
	v_lshl_add_u64 v[0:1], v[2:3], 0, v[0:1]
	s_waitcnt lgkmcnt(4)
	v_mov_b32_e32 v2, v19
	s_waitcnt lgkmcnt(3)
	v_mov_b32_e32 v3, v20
	v_mov_b32_e32 v28, v21
	v_lshl_add_u64 v[0:1], v[0:1], 0, s[24:25]
	s_waitcnt lgkmcnt(2)
	v_mov_b32_e32 v29, v22
	v_mov_b32_e32 v30, v23
	s_waitcnt lgkmcnt(1)
	v_mov_b32_e32 v31, v24
	v_mov_b32_e32 v32, v25
	s_waitcnt lgkmcnt(0)
	v_mov_b32_e32 v33, v26
	v_lshl_add_u64 v[34:35], v[0:1], 0, v[184:185]
	s_cmp_lt_u32 s31, 64
	s_cbranch_scc1 .Lhyt_w0
	s_waitcnt vmcnt(1)
	s_branch .Lhyt_wj
.Lhyt_w0:
	s_waitcnt vmcnt(2)
; __device__ __forceinline__ u32x4 zero4() { unsigned z = 0; asm volatile("" : "+v"(z)); return (u32x4){z, z, z, z}; }
; __device__ __forceinline__ unsigned cvt_pk_bf16(float lo, float hi) { const f32x2_t v = {lo, hi}; const bf16x2_t b = __builtin_convertvector(v, bf16x2_t); return __builtin_bit_cast(unsigned, b); }
; __device__ __forceinline__ float lo_bf(unsigned w) { return __uint_as_float(w << 16); }
; __device__ __forceinline__ float hi_bf(unsigned w) { return __uint_as_float(w & 0xffff0000u); }
; __device__ void hy_transpose_phase(unsigned char* smem, const Params& p, int l) {
;     ...
;         const int cblk = t % (HYC / 64), rblk = t / (HYC / 64); const int b = rblk >> 5, t0 = (rblk & 31) * 64, c0 = cblk * 64;
;         __syncthreads();
;         for (int e = tid; e < 66 * 8; e += 512) { const int rr = e >> 3, c8 = e & 7; const int tt = t0 - 1 + rr;
;             u32x4 v = zero4();
;             if (tt >= 0 && tt < SEQ) v = *(const u32x4*)(uhy + ((size_t)b * SEQ + tt) * HYC + c0 + c8 * 8);
;             float* d = tile + rr * 65 + c8 * 8;
;             d[0] = lo_bf(v.x); d[1] = hi_bf(v.x); d[2] = lo_bf(v.y); d[3] = hi_bf(v.y); d[4] = lo_bf(v.z); d[5] = hi_bf(v.z); d[6] = lo_bf(v.w); d[7] = hi_bf(v.w); }
;         __syncthreads();
;         { const int cc = tid >> 3, t8 = tid & 7, c = c0 + cc; const float w0 = cw[c], w1 = cw[HYC + c], w2 = cw[2 * HYC + c], bb = cb[c];
;           float x[10];
; #pragma unroll
;           for (int i = 0; i < 10; ++i) x[i] = tile[(t8 * 8 + i) * 65 + cc];
;           float o[8];
; #pragma unroll
;           for (int i = 0; i < 8; ++i) o[i] = w0 * x[i] + w1 * x[i + 1] + w2 * x[i + 2] + bb;
;           u32x4 w; w.x = cvt_pk_bf16(o[0], o[1]); w.y = cvt_pk_bf16(o[2], o[3]); w.z = cvt_pk_bf16(o[4], o[5]); w.w = cvt_pk_bf16(o[6], o[7]);
;           *(u32x4*)(hyT + ((size_t)c * NB + b) * SEQ + t0 + t8 * 8) = w; }
.Lhyt_wj:
	s_add_i32 s15, s15, s14
	s_cmpk_gt_i32 s15, 0x2fff
	v_pk_mul_f32 v[0:1], v[52:53], v[2:3] op_sel_hi:[0,1]
	v_pk_mul_f32 v[2:3], v[52:53], v[28:29] op_sel_hi:[0,1]
	v_pk_mul_f32 v[28:29], v[52:53], v[30:31] op_sel_hi:[0,1]
	v_pk_mul_f32 v[14:15], v[52:53], v[32:33] op_sel_hi:[0,1]
	v_pk_fma_f32 v[0:1], v[50:51], v[18:19], v[0:1] op_sel_hi:[0,1,1]
	v_pk_fma_f32 v[2:3], v[50:51], v[20:21], v[2:3] op_sel_hi:[0,1,1]
	v_pk_fma_f32 v[18:19], v[50:51], v[22:23], v[28:29] op_sel_hi:[0,1,1]
	v_pk_fma_f32 v[12:13], v[50:51], v[24:25], v[14:15] op_sel_hi:[0,1,1]
	v_pk_fma_f32 v[0:1], v[54:55], v[20:21], v[0:1] op_sel_hi:[0,1,1]
	v_pk_fma_f32 v[2:3], v[54:55], v[22:23], v[2:3] op_sel_hi:[0,1,1]
	v_pk_fma_f32 v[14:15], v[54:55], v[24:25], v[18:19] op_sel_hi:[0,1,1]
	v_pk_fma_f32 v[12:13], v[54:55], v[26:27], v[12:13] op_sel_hi:[0,1,1]
	v_pk_add_f32 v[0:1], v[56:57], v[0:1] op_sel_hi:[0,1]
	v_pk_add_f32 v[2:3], v[56:57], v[2:3] op_sel_hi:[0,1]
	v_pk_add_f32 v[14:15], v[56:57], v[14:15] op_sel_hi:[0,1]
	v_pk_add_f32 v[8:9], v[56:57], v[12:13] op_sel_hi:[0,1]
	v_cvt_pk_bf16_f32 v0, v0, v1
	v_cvt_pk_bf16_f32 v1, v2, v3
	v_cvt_pk_bf16_f32 v2, v14, v15
	v_cvt_pk_bf16_f32 v3, v8, v9
	global_store_dwordx4 v[34:35], v[0:3], off
	s_cbranch_scc1 .LBB0_259
.LBB0_252:
	s_mul_hi_i32 s12, s15, 0x2aaaaaab
	s_lshr_b32 s13, s12, 31
	s_ashr_i32 s20, s12, 2
	s_add_i32 s20, s20, s13
	s_ashr_i32 s12, s20, 5
	s_barrier
	s_and_saveexec_b64 s[16:17], s[0:1]
	s_xor_b64 s[16:17], exec, s[16:17]
	s_ashr_i32 s13, s12, 31
	s_or_saveexec_b64 s[18:19], s[16:17]
	s_mul_i32 s16, s20, 24
	s_sub_i32 s16, s15, s16
	s_lshl_b32 s17, s20, 6
	s_and_b32 s24, s17, 0x7c0
	s_lshl_b32 s16, s16, 6
	v_mov_b64_e32 v[0:1], s[12:13]
	v_add_u32_e32 v48, s16, v10
	v_ashrrev_i32_e32 v49, 31, v48
	v_lshlrev_b64 v[48:49], 2, v[48:49]
	v_lshl_add_u64 v[46:47], s[8:9], 0, v[48:49]
	s_mov_b64 s[22:23], 0x1800
	global_load_dword v50, v[46:47], off
	v_lshl_add_u64 v[44:45], v[46:47], 0, s[22:23]
	s_mov_b64 s[22:23], 0x3000
	global_load_dword v52, v[44:45], off
	v_lshl_add_u64 v[44:45], v[46:47], 0, s[22:23]
	global_load_dword v54, v[44:45], off
	v_lshl_add_u64 v[44:45], s[10:11], 0, v[48:49]
	global_load_dword v56, v[44:45], off
	s_xor_b64 exec, exec, s[18:19]
	s_cbranch_execz .LBB0_251
	s_waitcnt vmcnt(4)
	v_mul_u32_u24_e32 v14, 0x104, v10
	v_add_u32_e32 v14, v14, v6
	v_lshlrev_b32_e32 v13, 16, v36
	v_and_b32_e32 v0, 0xffff0000, v36
	ds_write2_b32 v14, v13, v0 offset1:1
	v_lshlrev_b32_e32 v0, 16, v37
	v_and_b32_e32 v1, 0xffff0000, v37
	ds_write2_b32 v14, v0, v1 offset0:2 offset1:3
	v_lshlrev_b32_e32 v0, 16, v38
	v_and_b32_e32 v1, 0xffff0000, v38
	ds_write2_b32 v14, v0, v1 offset0:4 offset1:5
	v_lshlrev_b32_e32 v0, 16, v39
	v_and_b32_e32 v1, 0xffff0000, v39
	ds_write2_b32 v14, v0, v1 offset0:6 offset1:7
	v_cmp_gt_u32_e32 vcc, 16, v7
	s_and_saveexec_b64 s[28:29], vcc
	v_add_u32_e32 v14, 0x4100, v14
	v_lshlrev_b32_e32 v13, 16, v40
	v_and_b32_e32 v0, 0xffff0000, v40
	ds_write2_b32 v14, v13, v0 offset1:1
	v_lshlrev_b32_e32 v0, 16, v41
	v_and_b32_e32 v1, 0xffff0000, v41
	ds_write2_b32 v14, v0, v1 offset0:2 offset1:3
	v_lshlrev_b32_e32 v0, 16, v42
	v_and_b32_e32 v1, 0xffff0000, v42
	ds_write2_b32 v14, v0, v1 offset0:4 offset1:5
	v_lshlrev_b32_e32 v0, 16, v43
	v_and_b32_e32 v1, 0xffff0000, v43
	ds_write2_b32 v14, v0, v1 offset0:6 offset1:7
	s_mov_b64 exec, s[28:29]
	s_add_i32 s98, s15, s14
	s_cmpk_gt_i32 s98, 0x2fff
	s_cbranch_scc1 .Lhyt_nopf
	s_mul_hi_i32 s99, s98, 0x2aaaaaab
	s_lshr_b32 s100, s99, 31
	s_ashr_i32 s99, s99, 2
	s_add_i32 s99, s99, s100
	s_mul_i32 s100, s99, 24
	s_sub_i32 s100, s98, s100
	s_lshl_b32 s100, s100, 7
	s_lshl_b32 s101, s99, 6
	s_and_b32 s101, s101, 0x7c0
	s_add_i32 s101, s101, -1
	s_ashr_i32 s99, s99, 5
	s_lshl_b32 s99, s99, 11
	v_add_u32_e32 v44, s101, v10
	v_add_u32_e32 v45, s99, v44
	v_mul_u32_u24_e32 v45, 0xc00, v45
	v_add_u32_e32 v46, s100, v45
	v_mov_b32_e32 v47, 0
	v_mov_b32_e32 v36, 0
	v_mov_b32_e32 v37, 0
	v_mov_b32_e32 v38, 0
	v_mov_b32_e32 v39, 0
	v_lshl_add_u64 v[46:47], v[4:5], 0, v[46:47]
	v_cmp_gt_u32_e32 vcc, 0x800, v44
	s_and_saveexec_b64 s[28:29], vcc
	global_load_dwordx4 v[36:39], v[46:47], off
	s_mov_b64 exec, s[28:29]
	s_cmp_lt_u32 s31, 64
	s_cbranch_scc0 .Lhyt_pf2_b
	v_add_u32_e32 v44, 64, v44
	v_add_u32_e32 v45, s99, v44
	v_mul_u32_u24_e32 v45, 0xc00, v45
	v_add_u32_e32 v46, s100, v45
	v_mov_b32_e32 v47, 0
	v_mov_b32_e32 v40, 0
	v_mov_b32_e32 v41, 0
	v_mov_b32_e32 v42, 0
	v_mov_b32_e32 v43, 0
	v_lshl_add_u64 v[46:47], v[4:5], 0, v[46:47]
	v_cmp_gt_u32_e32 vcc, 0x800, v44
	v_cmp_gt_u32_e64 s[34:35], 16, v7
	s_and_b64 vcc, vcc, s[34:35]
	s_and_saveexec_b64 s[28:29], vcc
	global_load_dwordx4 v[40:43], v[46:47], off
	s_mov_b64 exec, s[28:29]
.Lhyt_pf2_b:
	v_mov_b64_e32 v[0:1], s[12:13]
	s_branch .LBB0_251
.Lhyt_nopf:
	s_waitcnt vmcnt(0)
	v_mov_b64_e32 v[0:1], s[12:13]
	s_branch .LBB0_251
